# scan loops: bf16 LDS tiles XOR-swizzled (rows 4..11 of each 16-row group swap adjacent 16B chunks) so ds_read_b128 fragment reads are bank-conflict free
# speedup vs baseline: 1.0055x; 1.0055x over previous
.LBB0_338:
	s_or_b64 exec, exec, s[0:1]
	s_add_u32 s2, s68, 0x1c200000
	v_readlane_b32 s12, v254, 18
	s_addc_u32 s3, s69, 0
	s_lshr_b32 s10, s56, 7
	v_readlane_b32 s26, v254, 32
	v_readlane_b32 s20, v254, 26
	v_readlane_b32 s27, v254, 33
	s_add_u32 s11, s26, 0x6000000
	s_addc_u32 s20, s27, 0
	s_add_u32 s4, s68, 0x1d300000
	v_mov_b32_e32 v1, 0
	v_and_b32_e32 v57, 12, v2
	v_lshrrev_b32_e32 v2, 2, v186
	v_readlane_b32 s21, v254, 27
	s_addc_u32 s5, s69, 0
	s_bfe_u32 s0, s93, 0x30002
	v_and_b32_e32 v58, 12, v2
	v_lshlrev_b64 v[2:3], 1, v[0:1]
	v_lshlrev_b32_e32 v36, 4, v186
	v_readlane_b32 s22, v254, 28
	s_lshl_b32 s21, s0, 12
	s_lshl_b32 s0, s0, 8
	s_lshl_b32 s1, s6, 6
	v_lshl_add_u64 v[4:5], s[26:27], 0, v[2:3]
	v_and_b32_e32 v0, 0xf0, v36
	v_readlane_b32 s13, v254, 19
	s_bfe_u32 s12, s56, 0x10006
	s_or_b32 s22, s0, s1
	v_lshl_add_u64 v[4:5], v[4:5], 0, v[0:1]
	s_mov_b64 s[8:9], 0x4000000
	v_lshrrev_b32_e32 v104, 4, v186
	v_add_u32_e32 v59, 0x200, v186
	s_lshl_b32 s13, s12, 6
	v_lshl_add_u64 v[102:103], v[4:5], 0, s[8:9]
	s_lshl_b32 s0, s22, 14
	v_or_b32_e32 v4, s21, v104
	v_lshrrev_b32_e32 v106, 4, v59
	s_add_u32 s8, s11, s0
	v_lshlrev_b32_e32 v4, 10, v4
	v_mov_b32_e32 v5, v1
	v_or_b32_e32 v6, s21, v106
	s_mov_b32 s1, 0
	s_addc_u32 s9, s20, 0
	v_lshl_add_u64 v[4:5], v[102:103], 0, v[4:5]
	v_lshlrev_b32_e32 v6, 10, v6
	v_mov_b32_e32 v7, v1
	s_lshl_b32 s0, s95, 5
	v_lshl_add_u64 v[2:3], s[68:69], 0, v[2:3]
	v_readlane_b32 s14, v254, 20
	v_lshl_add_u64 v[6:7], v[102:103], 0, v[6:7]
	global_load_dwordx4 v[24:27], v[4:5], off
	global_load_dwordx4 v[28:31], v[6:7], off
	v_lshl_add_u64 v[16:17], v[2:3], 0, s[0:1]
	s_lshl_b32 s0, s12, 7
	s_lshl_b32 s7, s22, 13
	v_or_b32_e32 v4, s21, v184
	v_readlane_b32 s15, v254, 21
	s_add_u32 s14, s2, s7
	v_lshlrev_b32_e32 v4, 5, v4
	v_mov_b32_e32 v5, v1
	v_readlane_b32 s16, v254, 22
	s_addc_u32 s15, s3, 0
	v_lshl_add_u64 v[4:5], s[4:5], 0, v[4:5]
	s_lshl_b32 s6, s6, 3
	s_mov_b32 s7, s1
	v_readlane_b32 s17, v254, 23
	v_lshl_add_u64 v[4:5], v[4:5], 0, s[6:7]
	s_or_b32 s16, s21, 64
	global_load_dwordx4 v[32:35], v36, s[8:9]
	global_load_dwordx4 v[48:51], v36, s[14:15]
	global_load_dwordx2 v[118:119], v[4:5], off
	s_or_b32 s17, s22, 1
	v_or_b32_e32 v4, s16, v104
	s_lshl_b32 s14, s17, 14
	v_lshlrev_b32_e32 v4, 10, v4
	v_mov_b32_e32 v5, v1
	v_add_lshl_u32 v6, s16, v106, 10
	v_mov_b32_e32 v7, v1
	v_and_b32_e32 v56, 60, v186
	v_lshlrev_b32_e32 v12, 4, v59
	s_add_u32 s14, s11, s14
	v_lshl_add_u64 v[4:5], v[102:103], 0, v[4:5]
	v_lshl_add_u64 v[8:9], v[102:103], 0, v[6:7]
	v_lshlrev_b32_e32 v18, 1, v57
	v_mov_b32_e32 v19, v1
	s_addc_u32 s15, s20, 0
	global_load_dwordx4 v[4:7], v[4:5], off
	s_nop 0
	global_load_dwordx4 v[8:11], v[8:9], off
	s_nop 0
	global_load_dwordx4 v[44:47], v12, s[8:9]
	s_nop 0
	global_load_dwordx4 v[12:15], v12, s[14:15]
	v_lshl_add_u64 v[16:17], v[16:17], 0, v[18:19]
	s_mov_b64 s[8:9], 0x7201800
	v_or_b32_e32 v187, s21, v56
	v_readlane_b32 s24, v254, 30
	v_lshl_add_u64 v[108:109], v[16:17], 0, s[8:9]
	v_lshlrev_b32_e32 v42, 13, v187
	v_mov_b32_e32 v43, v1
	v_lshl_add_u64 v[42:43], v[108:109], 0, v[42:43]
	s_movk_i32 s24, 0x2000
	v_readlane_b32 s25, v254, 31
	v_or_b32_e32 v40, s16, v184
	v_add_co_u32_e32 v52, vcc, s24, v42
	v_lshlrev_b32_e32 v40, 5, v40
	v_mov_b32_e32 v41, v1
	v_addc_co_u32_e32 v53, vcc, 0, v43, vcc
	s_movk_i32 s25, 0x4000
	s_lshl_b32 s8, s17, 13
	v_lshl_add_u64 v[40:41], s[4:5], 0, v[40:41]
	v_add_co_u32_e32 v54, vcc, s25, v42
	s_add_u32 s8, s2, s8
	v_lshl_add_u64 v[40:41], v[40:41], 0, s[6:7]
	v_addc_co_u32_e32 v55, vcc, 0, v43, vcc
	s_movk_i32 s26, 0x6000
	s_addc_u32 s9, s3, 0
	global_load_dwordx4 v[16:19], v36, s[14:15]
	global_load_dwordx4 v[20:23], v36, s[8:9]
	global_load_dwordx2 v[114:115], v[40:41], off
	global_load_dwordx2 v[154:155], v[42:43], off
	global_load_dwordx2 v[150:151], v[52:53], off
	global_load_dwordx2 v[152:153], v[54:55], off
	v_add_co_u32_e32 v40, vcc, s26, v42
	v_mbcnt_lo_u32_b32 v53, -1, 0
	s_nop 0
	v_addc_co_u32_e32 v41, vcc, 0, v43, vcc
	global_load_dwordx2 v[156:157], v[40:41], off
	v_and_b32_e32 v39, 15, v186
	v_mbcnt_hi_u32_b32 v53, -1, v53
	v_bfrev_b32_e32 v55, 0.5
	v_lshlrev_b32_e32 v40, 1, v58
	v_mov_b32_e32 v41, v1
	v_lshl_add_u64 v[2:3], v[2:3], 0, s[0:1]
	v_and_b32_e32 v54, 64, v53
	v_lshl_or_b32 v191, v53, 2, v55
	v_lshl_or_b32 v55, s10, 4, v39
	s_add_u32 s6, s4, s6
	v_mov_b32_e32 v37, v1
	v_lshl_add_u64 v[2:3], v[2:3], 0, v[40:41]
	v_add_u32_e32 v255, 4, v186
	v_and_b32_e32 v255, 8, v255
	v_lshlrev_b32_e32 v255, 1, v255
	v_xor_b32_e32 v40, v40, v255
	v_add_u32_e32 v41, 0, v0
	v_lshrrev_b32_e32 v255, 4, v186
	v_add_u32_e32 v255, 4, v255
	v_and_b32_e32 v255, 8, v255
	v_lshlrev_b32_e32 v255, 1, v255
	v_xor_b32_e32 v41, v41, v255
	v_and_b32_e32 v0, 0x70, v36
	v_lshl_add_u32 v52, v56, 1, 0
	v_and_b32_e32 v255, 3, v186
	v_add_u32_e32 v255, 1, v255
	v_and_b32_e32 v255, 2, v255
	v_lshlrev_b32_e32 v255, 3, v255
	v_xor_b32_e32 v52, v52, v255
	v_and_or_b32 v56, v55, 63, v54
	s_addc_u32 s7, s5, 0
	s_add_i32 s4, 0, 0x10100
	v_add_u32_e32 v42, 0, v0
	v_lshrrev_b32_e32 v255, 3, v186
	v_add_u32_e32 v255, 4, v255
	v_and_b32_e32 v255, 8, v255
	v_lshlrev_b32_e32 v255, 1, v255
	v_xor_b32_e32 v42, v42, v255
	v_lshrrev_b32_e32 v0, 3, v186
	s_movk_i32 s0, 0x90
	v_lshlrev_b32_e32 v192, 2, v56
	v_lshl_add_u64 v[112:113], s[2:3], 0, v[36:37]
	s_movk_i32 s2, 0x110
	v_mov_b32_e32 v56, s4
	v_mul_u32_u24_e32 v43, 0x90, v0
	v_mad_u32_u24 v190, v0, s0, v42
	v_lshl_or_b32 v0, s95, 4, v57
	v_mad_u32_u24 v195, v39, s2, v56
	v_or_b32_e32 v56, v54, v39
	v_xor_b32_e32 v57, 16, v53
	v_add_u32_e32 v54, 64, v54
	s_add_i32 s5, 0, 0x19a00
	s_lshl_b32 s27, s12, 3
	s_mov_b64 s[8:9], 0x7201c00
	v_cmp_lt_i32_e32 vcc, v57, v54
	s_cmp_eq_u32 s12, 0
	v_lshl_add_u64 v[110:111], v[2:3], 0, s[8:9]
	v_and_b32_e32 v194, 48, v186
	v_add_u32_e32 v255, 4, v186
	v_and_b32_e32 v255, 8, v255
	v_lshlrev_b32_e32 v255, 1, v255
	v_xor_b32_e32 v194, v194, v255
	v_cndmask_b32_e32 v57, v53, v57, vcc
	v_lshl_add_u32 v200, v55, 4, s5
	s_cselect_b64 s[8:9], -1, 0
	s_lshl_b32 s5, s10, 6
	v_add_u32_e32 v197, s4, v194
	v_lshlrev_b32_e32 v198, 2, v57
	v_xor_b32_e32 v57, 32, v53
	s_add_i32 s4, s5, s4
	v_cmp_lt_i32_e32 vcc, v57, v54
	v_add_u32_e32 v54, s4, v40
	s_lshl_b32 s4, s12, 8
	s_add_i32 s4, s4, 0
	v_mul_lo_u32 v36, v55, s0
	v_cndmask_b32_e32 v53, v53, v57, vcc
	s_add_i32 s4, s4, 0x19e00
	v_lshlrev_b32_e32 v38, 3, v59
	v_add_u32_e32 v193, 0, v36
	v_mad_u32_u24 v37, v39, s0, 0
	v_lshlrev_b32_e32 v199, 2, v53
	v_lshl_or_b32 v53, s10, 5, v39
	v_or_b32_e32 v39, s13, v39
	v_add3_u32 v201, v195, s5, v40
	v_lshl_add_u32 v202, v58, 2, s4
	v_lshrrev_b32_e32 v58, 3, v59
	v_mul_lo_u32 v59, v0, s0
	v_or3_b32 v0, v184, s13, 48
	s_mov_b64 s[4:5], 0x17200000
	v_lshl_add_u32 v36, v55, 7, v193
	v_lshlrev_b32_e32 v196, 2, v56
	v_add_u32_e32 v56, 0, v194
	v_mul_u32_u24_e32 v40, 0x110, v104
	v_mul_u32_u24_e32 v57, 0x110, v106
	v_mul_u32_u24_e32 v58, 0x90, v58
	v_mul_u32_u24_e32 v60, 0x90, v39
	v_mul_u32_u24_e32 v203, 0x110, v39
	v_mul_u32_u24_e32 v39, 0x90, v0
	v_mul_u32_u24_e32 v61, 0x110, v0
	v_mov_b32_e32 v0, 0x80000
	v_lshl_add_u64 v[116:117], v[2:3], 0, s[4:5]
	v_mov_b32_e32 v2, v1
	v_mov_b32_e32 v3, v1
	v_readlane_b32 s23, v254, 29
	v_mul_lo_u32 v53, v53, s0
	v_lshl_or_b32 v204, v187, 12, v0
	v_mov_b32_e32 v0, v1
	v_lshlrev_b32_e32 v206, 1, v38
	v_add_u32_e32 v207, v41, v40
	v_add_u32_e32 v208, v42, v43
	v_add_u32_e32 v209, v41, v57
	v_add_u32_e32 v210, v42, v58
	v_add_u32_e32 v212, v36, v194
	v_add_u32_e32 v213, v37, v194
	v_add_u32_e32 v215, v56, v39
	v_mov_b64_e32 v[38:39], v[2:3]
	v_mov_b64_e32 v[42:43], v[2:3]
	v_lshlrev_b32_e32 v100, 3, v186
	v_mov_b32_e32 v101, v1
	v_mov_b32_e32 v105, v1
	v_mov_b32_e32 v107, v1
	v_cmp_gt_u32_e64 s[2:3], 16, v184
	v_add_u32_e32 v205, s21, v55
	v_mov_b32_e32 v219, 0xf149f2ca
	s_brev_b32 s10, 60
	v_add_u32_e32 v211, v52, v59
	v_add_u32_e32 v214, v56, v60
	v_add_u32_e32 v216, v197, v61
	v_add_u32_e32 v217, v56, v53
	v_add_u32_e32 v218, v54, v203
	s_mov_b32 s23, s66
	v_mov_b64_e32 v[36:37], v[0:1]
	v_mov_b64_e32 v[40:41], v[0:1]
	s_mov_b32 s28, 0
	v_mov_b32_e32 v126, v1
	v_mov_b32_e32 v127, v1
	v_mov_b32_e32 v124, v1
	v_mov_b32_e32 v125, v1
	v_mov_b32_e32 v120, v1
	v_mov_b32_e32 v121, v1
	v_mov_b32_e32 v130, v1
	v_mov_b32_e32 v131, v1
	v_mov_b32_e32 v122, v1
	v_mov_b32_e32 v123, v1
	v_mov_b32_e32 v132, v1
	v_mov_b32_e32 v133, v1
	v_mov_b32_e32 v128, v1
	v_mov_b32_e32 v129, v1
	v_mov_b32_e32 v138, v1
	v_mov_b32_e32 v139, v1
	v_mov_b32_e32 v134, v1
	v_mov_b32_e32 v135, v1
	v_mov_b32_e32 v142, v1
	v_mov_b32_e32 v143, v1
	v_mov_b32_e32 v136, v1
	v_mov_b32_e32 v137, v1
	v_mov_b32_e32 v146, v1
	v_mov_b32_e32 v147, v1
	v_mov_b32_e32 v140, v1
	v_mov_b32_e32 v141, v1
	v_mov_b32_e32 v148, v1
	v_mov_b32_e32 v149, v1
	v_mov_b32_e32 v144, v1
	v_mov_b32_e32 v145, v1
	v_readlane_b32 s18, v254, 24
	v_readlane_b32 s19, v254, 25
	s_waitcnt vmcnt(0) lgkmcnt(0)
	s_barrier

.LBB0_376:
	s_or_b64 exec, exec, s[0:1]
	s_bfe_u32 s0, s93, 0x30002
	s_add_u32 s2, s68, 0x1b200000
	v_readlane_b32 s8, v254, 18
	s_addc_u32 s3, s69, 0
	s_lshr_b32 s6, s56, 7
	v_readlane_b32 s14, v254, 24
	v_readlane_b32 s22, v254, 32
	v_readlane_b32 s15, v254, 25
	v_readlane_b32 s23, v254, 33
	s_add_u32 s14, s22, 0x2000000
	s_addc_u32 s15, s23, 0
	v_readlane_b32 s12, v254, 22
	v_readlane_b32 s16, v254, 26
	s_add_u32 s7, s68, 0x1d200000
	v_readlane_b32 s17, v254, 27
	s_addc_u32 s12, s69, 0
	s_lshl_b32 s16, s0, 12
	s_lshl_b32 s0, s0, 8
	s_lshl_b32 s1, s4, 6
	s_bfe_u32 s5, s56, 0x10006
	s_or_b32 s17, s0, s1
	v_mov_b32_e32 v73, 0
	s_lshl_b32 s4, s5, 6
	v_lshrrev_b32_e32 v0, 2, v186
	v_lshlrev_b64 v[4:5], 1, v[72:73]
	v_lshlrev_b32_e32 v48, 4, v186
	s_lshl_b32 s0, s17, 14
	v_readlane_b32 s9, v254, 19
	v_and_b32_e32 v84, 12, v0
	v_lshl_add_u64 v[0:1], s[22:23], 0, v[4:5]
	v_and_b32_e32 v72, 0xf0, v48
	s_add_u32 s8, s14, s0
	v_lshrrev_b32_e32 v78, 4, v186
	v_add_u32_e32 v91, 0x200, v186
	v_readlane_b32 s10, v254, 20
	s_mov_b32 s1, 0
	v_lshl_add_u64 v[76:77], v[0:1], 0, v[72:73]
	s_addc_u32 s9, s15, 0
	v_or_b32_e32 v0, s16, v78
	v_lshrrev_b32_e32 v80, 4, v91
	s_lshl_b32 s0, s95, 5
	v_lshl_add_u64 v[52:53], s[68:69], 0, v[4:5]
	v_lshlrev_b32_e32 v0, 10, v0
	v_mov_b32_e32 v1, v73
	v_or_b32_e32 v2, s16, v80
	v_lshl_add_u64 v[20:21], v[52:53], 0, s[0:1]
	s_lshl_b32 s0, s5, 7
	s_lshl_b32 s10, s17, 13
	v_readlane_b32 s11, v254, 21
	v_lshl_add_u64 v[0:1], v[76:77], 0, v[0:1]
	v_lshlrev_b32_e32 v2, 10, v2
	v_mov_b32_e32 v3, v73
	s_add_u32 s10, s2, s10
	v_lshl_add_u64 v[6:7], v[76:77], 0, v[2:3]
	global_load_dwordx4 v[0:3], v[0:1], off
	s_nop 0
	global_load_dwordx4 v[24:27], v[6:7], off
	s_addc_u32 s11, s3, 0
	global_load_dwordx4 v[16:19], v48, s[8:9]
	global_load_dwordx4 v[40:43], v48, s[10:11]
	s_lshl_b32 s10, s17, 9
	v_readlane_b32 s13, v254, 23
	s_add_u32 s10, s7, s10
	s_addc_u32 s11, s12, 0
	s_and_b32 s13, s56, 0xffffff80
	v_readlane_b32 s18, v254, 28
	s_add_u32 s10, s10, s13
	v_readlane_b32 s19, v254, 29
	s_addc_u32 s11, s11, 0
	s_or_b32 s18, s16, 64
	v_lshlrev_b32_e32 v90, 2, v184
	v_lshlrev_b32_e32 v54, 2, v84
	s_or_b32 s19, s17, 1
	v_or_b32_e32 v4, s18, v78
	v_and_b32_e32 v87, 12, v90
	global_load_dwordx4 v[60:63], v54, s[10:11]
	global_load_dwordx4 v[56:59], v54, s[10:11] offset:64
	s_lshl_b32 s10, s19, 14
	v_lshlrev_b32_e32 v4, 10, v4
	v_mov_b32_e32 v5, v73
	v_add_lshl_u32 v6, s18, v80, 10
	v_mov_b32_e32 v7, v73
	v_and_b32_e32 v86, 60, v186
	v_lshlrev_b32_e32 v12, 4, v91
	s_add_u32 s10, s14, s10
	v_lshl_add_u64 v[4:5], v[76:77], 0, v[4:5]
	v_lshl_add_u64 v[8:9], v[76:77], 0, v[6:7]
	v_lshlrev_b32_e32 v22, 1, v87
	v_mov_b32_e32 v23, v73
	s_addc_u32 s11, s15, 0
	global_load_dwordx4 v[4:7], v[4:5], off
	s_nop 0
	global_load_dwordx4 v[8:11], v[8:9], off
	s_nop 0
	global_load_dwordx4 v[44:47], v12, s[8:9]
	s_nop 0
	global_load_dwordx4 v[12:15], v12, s[10:11]
	v_lshl_add_u64 v[20:21], v[20:21], 0, v[22:23]
	s_mov_b64 s[8:9], 0x7200800
	v_or_b32_e32 v79, s16, v86
	v_lshl_add_u64 v[82:83], v[20:21], 0, s[8:9]
	s_lshl_b32 s8, s19, 13
	v_lshlrev_b32_e32 v64, 13, v79
	v_mov_b32_e32 v65, v73
	s_add_u32 s8, s2, s8
	v_lshl_add_u64 v[64:65], v[82:83], 0, v[64:65]
	s_movk_i32 s18, 0x2000
	s_addc_u32 s9, s3, 0
	global_load_dwordx4 v[20:23], v48, s[10:11]
	global_load_dwordx4 v[28:31], v48, s[8:9]
	s_lshl_b32 s8, s19, 9
	v_add_co_u32_e32 v66, vcc, s18, v64
	s_add_u32 s8, s7, s8
	s_nop 0
	v_addc_co_u32_e32 v67, vcc, 0, v65, vcc
	s_movk_i32 s19, 0x4000
	v_readlane_b32 s20, v254, 30
	s_addc_u32 s9, s12, 0
	v_add_co_u32_e32 v68, vcc, s19, v64
	s_add_u32 s8, s8, s13
	s_nop 0
	v_addc_co_u32_e32 v69, vcc, 0, v65, vcc
	s_movk_i32 s20, 0x6000
	s_addc_u32 s9, s9, 0
	v_add_co_u32_e32 v70, vcc, s20, v64
	global_load_dwordx4 v[36:39], v54, s[8:9]
	global_load_dwordx4 v[32:35], v54, s[8:9] offset:64
	v_addc_co_u32_e32 v71, vcc, 0, v65, vcc
	global_load_dwordx2 v[124:125], v[64:65], off
	global_load_dwordx2 v[130:131], v[66:67], off
	global_load_dwordx2 v[126:127], v[68:69], off
	global_load_dwordx2 v[128:129], v[70:71], off
	v_lshlrev_b32_e32 v64, 1, v84
	v_mov_b32_e32 v65, v73
	v_lshl_add_u64 v[52:53], v[52:53], 0, s[0:1]
	v_lshl_add_u64 v[52:53], v[52:53], 0, v[64:65]
	s_mov_b64 s[8:9], 0x7200c00
	v_lshl_add_u64 v[84:85], v[52:53], 0, s[8:9]
	v_and_b32_e32 v66, 0x70, v48
	s_add_u32 s8, s7, s13
	v_mov_b32_e32 v49, v73
	v_add_u32_e32 v66, 0, v66
	v_lshrrev_b32_e32 v255, 3, v186
	v_add_u32_e32 v255, 4, v255
	v_and_b32_e32 v255, 8, v255
	v_lshlrev_b32_e32 v255, 1, v255
	v_xor_b32_e32 v66, v66, v255
	v_lshrrev_b32_e32 v67, 3, v186
	s_movk_i32 s0, 0x90
	s_addc_u32 s9, s12, 0
	s_lshl_b32 s7, s6, 6
	s_lshl_b32 s10, s5, 1
	v_mul_u32_u24_e32 v68, 0x90, v67
	v_mad_u32_u24 v160, v67, s0, v66
	v_lshl_or_b32 v67, s95, 4, v87
	v_lshl_add_u32 v69, v86, 1, 0
	v_and_b32_e32 v255, 3, v186
	v_add_u32_e32 v255, 1, v255
	v_and_b32_e32 v255, 2, v255
	v_lshlrev_b32_e32 v255, 3, v255
	v_xor_b32_e32 v69, v69, v255
	v_lshl_add_u64 v[86:87], s[2:3], 0, v[48:49]
	s_mov_b64 s[2:3], 0x17200000
	s_or_b32 s10, s10, s7
	v_and_b32_e32 v51, 15, v186
	v_lshl_add_u64 v[88:89], v[52:53], 0, s[2:3]
	v_or_b32_e32 v52, s10, v90
	s_add_i32 s10, 0, 0x18000
	v_readlane_b32 s21, v254, 31
	v_lshl_or_b32 v48, s6, 4, v51
	v_lshl_add_u32 v164, v52, 2, s10
	v_lshl_or_b32 v52, s6, 5, v51
	s_add_i32 s6, s7, 0
	v_add_u32_e32 v65, 0, v72
	v_lshrrev_b32_e32 v255, 4, v186
	v_add_u32_e32 v255, 4, v255
	v_and_b32_e32 v255, 8, v255
	v_lshlrev_b32_e32 v255, 1, v255
	v_xor_b32_e32 v65, v65, v255
	v_or_b32_e32 v51, s4, v51
	v_add_u32_e32 v165, s6, v64
	v_add_u32_e32 v255, 4, v186
	v_and_b32_e32 v255, 8, v255
	v_lshlrev_b32_e32 v255, 1, v255
	v_xor_b32_e32 v165, v165, v255
	s_lshl_b32 s6, s5, 8
	s_lshl_b32 s21, s5, 3
	s_movk_i32 s5, 0x110
	v_mov_b32_e32 v72, 0x1100
	v_mul_lo_u32 v49, v48, s0
	v_mad_u32_u24 v169, v51, s5, v72
	v_mov_b32_e32 v72, 0x2200
	v_add_u32_e32 v161, 0, v49
	v_and_b32_e32 v162, 48, v186
	v_add_u32_e32 v255, 4, v186
	v_and_b32_e32 v255, 8, v255
	v_lshlrev_b32_e32 v255, 1, v255
	v_xor_b32_e32 v162, v162, v255
	s_add_i32 s6, s6, 0
	v_lshrrev_b32_e32 v70, 3, v91
	v_mul_u32_u24_e32 v71, 0x90, v51
	v_mul_u32_u24_e32 v168, 0x110, v51
	v_mad_u32_u24 v170, v51, s5, v72
	v_or3_b32 v72, v184, s4, 48
	v_or_b32_e32 v51, 48, v51
	v_lshlrev_b32_e32 v50, 3, v91
	v_mov_b32_e32 v55, v73
	v_lshl_add_u32 v49, v48, 7, v161
	v_add_u32_e32 v163, 0, v162
	v_lshl_add_u32 v166, v48, 4, s10
	s_add_i32 s6, s6, 0x18400
	v_mul_u32_u24_e32 v53, 0x110, v78
	v_mul_u32_u24_e32 v64, 0x110, v80
	v_mul_u32_u24_e32 v70, 0x90, v70
	v_mul_lo_u32 v67, v67, s0
	v_mul_u32_u24_e32 v92, 0x90, v72
	v_mul_u32_u24_e32 v72, 0x110, v72
	v_mul_lo_u32 v52, v52, s0
	v_mul_u32_u24_e32 v51, 0x110, v51
	v_mov_b32_e32 v90, 0x80000
	v_add_u32_e32 v172, s16, v48
	v_mbcnt_lo_u32_b32 v48, -1, 0
	v_lshlrev_b32_e32 v74, 3, v186
	v_mov_b32_e32 v75, v73
	v_mov_b32_e32 v81, v73
	v_cmp_gt_u32_e64 s[2:3], 16, v184
	v_add_u32_e32 v167, s6, v54
	v_lshl_or_b32 v171, v79, 12, v90
	v_lshl_add_u64 v[90:91], s[8:9], 0, v[54:55]
	v_lshlrev_b32_e32 v173, 1, v50
	v_mbcnt_hi_u32_b32 v174, -1, v48
	v_add_u32_e32 v175, v65, v53
	v_add_u32_e32 v176, v66, v68
	v_add_u32_e32 v177, v65, v64
	v_add_u32_e32 v178, v66, v70
	v_add_u32_e32 v179, v69, v67
	v_add_u32_e32 v180, v49, v162
	v_add_u32_e32 v181, v163, v71
	v_add_u32_e32 v182, v163, v92
	v_add_u32_e32 v183, v163, v72
	v_add_u32_e32 v187, v163, v52
	v_add_u32_e32 v188, v165, v51
	s_mov_b32 s22, 0
	v_mov_b32_e32 v92, v73
	v_mov_b32_e32 v93, v73
	v_mov_b32_e32 v98, v73
	v_mov_b32_e32 v99, v73
	v_mov_b32_e32 v94, v73
	v_mov_b32_e32 v95, v73
	v_mov_b32_e32 v96, v73
	v_mov_b32_e32 v97, v73
	v_mov_b32_e32 v100, v73
	v_mov_b32_e32 v101, v73
	v_mov_b32_e32 v104, v73
	v_mov_b32_e32 v105, v73
	v_mov_b32_e32 v102, v73
	v_mov_b32_e32 v103, v73
	v_mov_b32_e32 v106, v73
	v_mov_b32_e32 v107, v73
	v_mov_b32_e32 v108, v73
	v_mov_b32_e32 v109, v73
	v_mov_b32_e32 v112, v73
	v_mov_b32_e32 v113, v73
	v_mov_b32_e32 v110, v73
	v_mov_b32_e32 v111, v73
	v_mov_b32_e32 v116, v73
	v_mov_b32_e32 v117, v73
	v_mov_b32_e32 v114, v73
	v_mov_b32_e32 v115, v73
	v_mov_b32_e32 v120, v73
	v_mov_b32_e32 v121, v73
	v_mov_b32_e32 v118, v73
	v_mov_b32_e32 v119, v73
	v_mov_b32_e32 v122, v73
	v_mov_b32_e32 v123, v73
	s_waitcnt vmcnt(0) lgkmcnt(0)
	s_barrier

	.amdhsa_kernel _Z14fwd_megakernel4Args
		.amdhsa_group_segment_fixed_size 0
		.amdhsa_private_segment_fixed_size 0
		.amdhsa_kernarg_size 464
		.amdhsa_user_sgpr_count 2
		.amdhsa_user_sgpr_dispatch_ptr 0
		.amdhsa_user_sgpr_queue_ptr 0
		.amdhsa_user_sgpr_kernarg_segment_ptr 1
		.amdhsa_user_sgpr_dispatch_id 0
		.amdhsa_user_sgpr_kernarg_preload_length 0
		.amdhsa_user_sgpr_kernarg_preload_offset 0
		.amdhsa_user_sgpr_private_segment_size 0
		.amdhsa_uses_dynamic_stack 0
		.amdhsa_enable_private_segment 0
		.amdhsa_system_sgpr_workgroup_id_x 1
		.amdhsa_system_sgpr_workgroup_id_y 0
		.amdhsa_system_sgpr_workgroup_id_z 0
		.amdhsa_system_sgpr_workgroup_info 0
		.amdhsa_system_vgpr_workitem_id 2
		.amdhsa_next_free_vgpr 256
		.amdhsa_next_free_sgpr 98
		.amdhsa_accum_offset 256
		.amdhsa_reserve_vcc 1
		.amdhsa_float_round_mode_32 0
		.amdhsa_float_round_mode_16_64 0
		.amdhsa_float_denorm_mode_32 3
		.amdhsa_float_denorm_mode_16_64 3
		.amdhsa_dx10_clamp 1
		.amdhsa_ieee_mode 1
		.amdhsa_fp16_overflow 0
		.amdhsa_tg_split 0
		.amdhsa_exception_fp_ieee_invalid_op 0
		.amdhsa_exception_fp_denorm_src 0
		.amdhsa_exception_fp_ieee_div_zero 0
		.amdhsa_exception_fp_ieee_overflow 0
		.amdhsa_exception_fp_ieee_underflow 0
		.amdhsa_exception_fp_ieee_inexact 0
		.amdhsa_exception_int_div_zero 0
	.end_amdhsa_kernel

amdhsa.kernels:
  - .agpr_count:     0
    .args:
      - .offset:         0
        .size:           208
        .value_kind:     by_value
      - .offset:         208
        .size:           4
        .value_kind:     hidden_block_count_x
      - .offset:         212
        .size:           4
        .value_kind:     hidden_block_count_y
      - .offset:         216
        .size:           4
        .value_kind:     hidden_block_count_z
      - .offset:         220
        .size:           2
        .value_kind:     hidden_group_size_x
      - .offset:         222
        .size:           2
        .value_kind:     hidden_group_size_y
      - .offset:         224
        .size:           2
        .value_kind:     hidden_group_size_z
      - .offset:         226
        .size:           2
        .value_kind:     hidden_remainder_x
      - .offset:         228
        .size:           2
        .value_kind:     hidden_remainder_y
      - .offset:         230
        .size:           2
        .value_kind:     hidden_remainder_z
      - .offset:         248
        .size:           8
        .value_kind:     hidden_global_offset_x
      - .offset:         256
        .size:           8
        .value_kind:     hidden_global_offset_y
      - .offset:         264
        .size:           8
        .value_kind:     hidden_global_offset_z
      - .offset:         272
        .size:           2
        .value_kind:     hidden_grid_dims
      - .offset:         296
        .size:           8
        .value_kind:     hidden_multigrid_sync_arg
      - .offset:         328
        .size:           4
        .value_kind:     hidden_dynamic_lds_size
    .group_segment_fixed_size: 0
    .kernarg_segment_align: 8
    .kernarg_segment_size: 464
    .language:       OpenCL C
    .language_version:
      - 2
      - 0
    .max_flat_workgroup_size: 512
    .name:           _Z14fwd_megakernel4Args
    .private_segment_fixed_size: 0
    .sgpr_count:     104
    .sgpr_spill_count: 70
    .symbol:         _Z14fwd_megakernel4Args.kd
    .uniform_work_group_size: 1
    .uses_dynamic_stack: false
    .vgpr_count:     256
    .vgpr_spill_count: 0
    .wavefront_size: 64
